# v60 + P3b EpiGate rewritten by hand: G and O loads of 4 row blocks in flight with counted vmcnt, saddr addressing
# speedup vs baseline: 1.0165x; 1.0020x over previous
; #define PG8_STAGE(bufoff, gbase, voff) do { _Pragma("unroll") for (int _i = 0; _i < 2; ++_i) \
;         __builtin_amdgcn_global_load_lds((const unsigned*)((const char*)(gbase) + (voff)[_i]), (PG8_LAS unsigned*)(lds + (bufoff) + ldsw + _i * 8192), 16, 0, 0); } while (0)
; #define PG8_LDA(dst, b, h) do { _Pragma("unroll") for (int m = 0; m < 4; ++m) _Pragma("unroll") for (int k = 0; k < 2; ++k) dst[m][k] = *(const PG8_LAS bf16x8*)(lds + PG8_SA(b, h) + aoff + m * 2048 + k * 1024); } while (0)
; #define PG8_LDB(dst, b, h) do { _Pragma("unroll") for (int n = 0; n < 2; ++n) _Pragma("unroll") for (int k = 0; k < 2; ++k) dst[n][k] = *(const PG8_LAS bf16x8*)(lds + PG8_SB(b, h) + boff + n * 2048 + k * 1024); } while (0)
; #define PG8_MMA(ai, bj, At, Bt) do { __builtin_amdgcn_s_setprio(1); _Pragma("unroll") for (int m = 0; m < 4; ++m) _Pragma("unroll") for (int n = 0; n < 2; ++n) _Pragma("unroll") for (int k = 0; k < 2; ++k) \
;         acc[ai][bj][m][n] = __builtin_amdgcn_mfma_f32_16x16x32_bf16(Bt[n][k], At[m][k], acc[ai][bj][m][n], 0, 0, 0); __builtin_amdgcn_s_setprio(0); } while (0)
; #define PG8_WAIT_V(n) asm volatile("s_waitcnt vmcnt(" #n ")" ::: "memory")
; #define PG8_WAIT_L(n) asm volatile("s_waitcnt lgkmcnt(" #n ")" ::: "memory")
; #define PG8_BAR __builtin_amdgcn_s_barrier()
; #define PG8_SCHED __builtin_amdgcn_sched_barrier(0)
; template <class Epi, class Sched, bool ALIGN_EPI = false, bool SP2 = false>
; __device__ __forceinline__ void gemm_phase(PG8_LAS unsigned char* lds, const Gemm g, const Sched& S, const Epi& E) {
;     ...
;             PG8_WAIT_V(8); PG8_WAIT_L(0); PG8_BAR; PG8_MMA(0, 0, At, B0); PG8_MMA(0, 1, At, B1); PG8_BAR; PG8_SCHED;
;             PG8_LDA(At, 0, 1); PG8_STAGE(PG8_SB(0, 0), b2, voffB); PG8_STAGE(PG8_SB(0, 1), b2 + hstep, voffB); PG8_STAGE(PG8_SA(0, 0), a2, voffA);
;             PG8_WAIT_V(8); PG8_WAIT_L(0); PG8_BAR; PG8_MMA(1, 0, At, B0); PG8_MMA(1, 1, At, B1); PG8_BAR; PG8_SCHED;
;             PG8_LDB(B0, 1, 0); PG8_LDB(B1, 1, 1); PG8_SCHED; PG8_LDA(At, 1, 0); PG8_STAGE(PG8_SA(0, 1), a2 + hstep, voffA);
;             PG8_WAIT_V(8); PG8_WAIT_L(0); PG8_BAR; PG8_MMA(0, 0, At, B0); PG8_MMA(0, 1, At, B1); PG8_BAR; PG8_SCHED;
.Lrj_P3b_1:
	s_mov_b32 s99, 0
	s_waitcnt lgkmcnt(0)
	s_barrier
	s_setprio 1
	s_waitcnt lgkmcnt(0)
	v_mfma_f32_16x16x32_bf16 v[140:143], v[0:3], v[60:63], 0
	v_mfma_f32_16x16x32_bf16 v[158:161], v[0:3], v[104:107], 0
	v_mfma_f32_16x16x32_bf16 v[166:169], v[0:3], v[112:115], 0
	v_mfma_f32_16x16x32_bf16 v[0:3], v[0:3], v[120:123], 0
	v_mfma_f32_16x16x32_bf16 v[140:143], v[4:7], v[100:103], v[140:143]
	v_mfma_f32_16x16x32_bf16 v[158:161], v[4:7], v[108:111], v[158:161]
	v_mfma_f32_16x16x32_bf16 v[166:169], v[4:7], v[116:119], v[166:169]
	v_mfma_f32_16x16x32_bf16 v[0:3], v[4:7], v[124:127], v[0:3]
	v_mfma_f32_16x16x32_bf16 v[4:7], v[8:11], v[120:123], 0
	v_mfma_f32_16x16x32_bf16 v[154:157], v[8:11], v[60:63], 0
	v_mfma_f32_16x16x32_bf16 v[162:165], v[8:11], v[104:107], 0
	v_mfma_f32_16x16x32_bf16 v[170:173], v[8:11], v[112:115], 0
	v_mfma_f32_16x16x32_bf16 v[4:7], v[12:15], v[124:127], v[4:7]
	v_mfma_f32_16x16x32_bf16 v[154:157], v[12:15], v[100:103], v[154:157]
	v_mfma_f32_16x16x32_bf16 v[162:165], v[12:15], v[108:111], v[162:165]
	v_mfma_f32_16x16x32_bf16 v[170:173], v[12:15], v[116:119], v[170:173]
	s_setprio 0
	s_setprio 1
	v_mfma_f32_16x16x32_bf16 v[8:11], v[16:19], v[60:63], 0
	v_mfma_f32_16x16x32_bf16 v[12:15], v[24:27], v[60:63], 0
	v_mfma_f32_16x16x32_bf16 v[8:11], v[20:23], v[100:103], v[8:11]
	v_mfma_f32_16x16x32_bf16 v[12:15], v[28:31], v[100:103], v[12:15]
	v_mfma_f32_16x16x32_bf16 v[60:63], v[16:19], v[104:107], 0
	v_mfma_f32_16x16x32_bf16 v[100:103], v[24:27], v[104:107], 0
	v_mfma_f32_16x16x32_bf16 v[104:107], v[16:19], v[112:115], 0
	v_mfma_f32_16x16x32_bf16 v[16:19], v[16:19], v[120:123], 0
	v_mfma_f32_16x16x32_bf16 v[60:63], v[20:23], v[108:111], v[60:63]
	v_mfma_f32_16x16x32_bf16 v[100:103], v[28:31], v[108:111], v[100:103]
	v_mfma_f32_16x16x32_bf16 v[104:107], v[20:23], v[116:119], v[104:107]
	v_mfma_f32_16x16x32_bf16 v[108:111], v[24:27], v[112:115], 0
	v_mfma_f32_16x16x32_bf16 v[16:19], v[20:23], v[124:127], v[16:19]
	v_mfma_f32_16x16x32_bf16 v[20:23], v[24:27], v[120:123], 0
	v_mfma_f32_16x16x32_bf16 v[108:111], v[28:31], v[116:119], v[108:111]
	v_mfma_f32_16x16x32_bf16 v[20:23], v[28:31], v[124:127], v[20:23]
	s_setprio 0
	s_barrier
	s_add_i32 s37, 0, 0x1c000
	v_add_u32_e32 v153, s37, v147
	ds_read_b128 v[24:27], v152
	ds_read_b128 v[28:31], v152 offset:1024
	ds_read_b128 v[112:115], v152 offset:2048
	ds_read_b128 v[116:119], v152 offset:3072
	ds_read_b128 v[120:123], v153
	ds_read_b128 v[124:127], v153 offset:1024
	ds_read_b128 v[174:177], v153 offset:2048
	ds_read_b128 v[178:181], v153 offset:3072
	s_add_u32 s88, s52, 0x10100
	s_addc_u32 s89, s53, 0
	s_mov_b32 m0, s68
	v_lshl_add_u64 v[220:221], s[88:89], 0, v[134:135]
	ds_read_b128 v[182:185], v151 offset:32768
	ds_read_b128 v[186:189], v151 offset:33792
	ds_read_b128 v[190:193], v151 offset:34816
	ds_read_b128 v[194:197], v151 offset:35840
	ds_read_b128 v[198:201], v151 offset:36864
	ds_read_b128 v[202:205], v151 offset:37888
	ds_read_b128 v[206:209], v151 offset:38912
	ds_read_b128 v[210:213], v151 offset:39936
	global_load_lds_dwordx4 v[220:221], off
	v_lshl_add_u64 v[220:221], s[88:89], 0, v[130:131]
	s_mov_b32 m0, s69
	s_nop 0
	global_load_lds_dwordx4 v[220:221], off
	s_waitcnt vmcnt(8)
	s_waitcnt lgkmcnt(0)
	s_barrier
	s_setprio 1
	s_waitcnt lgkmcnt(0)
	v_mfma_f32_16x16x32_bf16 v[64:67], v[24:27], v[182:185], v[64:67]
	v_mfma_f32_16x16x32_bf16 v[68:71], v[112:115], v[182:185], v[68:71]
	v_mfma_f32_16x16x32_bf16 v[72:75], v[24:27], v[190:193], v[72:75]
	v_mfma_f32_16x16x32_bf16 v[76:79], v[112:115], v[190:193], v[76:79]
	v_mfma_f32_16x16x32_bf16 v[80:83], v[24:27], v[198:201], v[80:83]
	v_mfma_f32_16x16x32_bf16 v[84:87], v[112:115], v[198:201], v[84:87]
	v_mfma_f32_16x16x32_bf16 v[88:91], v[24:27], v[206:209], v[88:91]
	v_mfma_f32_16x16x32_bf16 v[92:95], v[112:115], v[206:209], v[92:95]
	v_mfma_f32_16x16x32_bf16 v[64:67], v[28:31], v[186:189], v[64:67]
	v_mfma_f32_16x16x32_bf16 v[68:71], v[116:119], v[186:189], v[68:71]
	v_mfma_f32_16x16x32_bf16 v[72:75], v[28:31], v[194:197], v[72:75]
	v_mfma_f32_16x16x32_bf16 v[76:79], v[116:119], v[194:197], v[76:79]
	v_mfma_f32_16x16x32_bf16 v[80:83], v[28:31], v[202:205], v[80:83]
	v_mfma_f32_16x16x32_bf16 v[84:87], v[116:119], v[202:205], v[84:87]
	v_mfma_f32_16x16x32_bf16 v[88:91], v[28:31], v[210:213], v[88:91]
	v_mfma_f32_16x16x32_bf16 v[92:95], v[116:119], v[210:213], v[92:95]
	s_setprio 0
	s_setprio 1
	v_mfma_f32_16x16x32_bf16 v[96:99], v[120:123], v[182:185], v[96:99]
	v_mfma_f32_16x16x32_bf16 v[32:35], v[174:177], v[182:185], v[32:35]
	v_mfma_f32_16x16x32_bf16 v[36:39], v[120:123], v[190:193], v[36:39]
	v_mfma_f32_16x16x32_bf16 v[40:43], v[174:177], v[190:193], v[40:43]
	v_mfma_f32_16x16x32_bf16 v[44:47], v[120:123], v[198:201], v[44:47]
	v_mfma_f32_16x16x32_bf16 v[48:51], v[174:177], v[198:201], v[48:51]
	v_mfma_f32_16x16x32_bf16 v[52:55], v[120:123], v[206:209], v[52:55]
	v_mfma_f32_16x16x32_bf16 v[56:59], v[174:177], v[206:209], v[56:59]
	v_mfma_f32_16x16x32_bf16 v[96:99], v[124:127], v[186:189], v[96:99]
	v_mfma_f32_16x16x32_bf16 v[32:35], v[178:181], v[186:189], v[32:35]
	v_mfma_f32_16x16x32_bf16 v[36:39], v[124:127], v[194:197], v[36:39]
	v_mfma_f32_16x16x32_bf16 v[40:43], v[178:181], v[194:197], v[40:43]
	v_mfma_f32_16x16x32_bf16 v[44:47], v[124:127], v[202:205], v[44:47]
	v_mfma_f32_16x16x32_bf16 v[48:51], v[178:181], v[202:205], v[48:51]
	v_mfma_f32_16x16x32_bf16 v[52:55], v[124:127], v[210:213], v[52:55]
	v_mfma_f32_16x16x32_bf16 v[56:59], v[178:181], v[210:213], v[56:59]
	s_setprio 0
	s_barrier
; #define PG8_STAGE(bufoff, gbase, voff) do { _Pragma("unroll") for (int _i = 0; _i < 2; ++_i) \
;         __builtin_amdgcn_global_load_lds((const unsigned*)((const char*)(gbase) + (voff)[_i]), (PG8_LAS unsigned*)(lds + (bufoff) + ldsw + _i * 8192), 16, 0, 0); } while (0)
; #define PG8_LDA(dst, b, h) do { _Pragma("unroll") for (int m = 0; m < 4; ++m) _Pragma("unroll") for (int k = 0; k < 2; ++k) dst[m][k] = *(const PG8_LAS bf16x8*)(lds + PG8_SA(b, h) + aoff + m * 2048 + k * 1024); } while (0)
; #define PG8_LDB(dst, b, h) do { _Pragma("unroll") for (int n = 0; n < 2; ++n) _Pragma("unroll") for (int k = 0; k < 2; ++k) dst[n][k] = *(const PG8_LAS bf16x8*)(lds + PG8_SB(b, h) + boff + n * 2048 + k * 1024); } while (0)
; #define PG8_MMA(ai, bj, At, Bt) do { __builtin_amdgcn_s_setprio(1); _Pragma("unroll") for (int m = 0; m < 4; ++m) _Pragma("unroll") for (int n = 0; n < 2; ++n) _Pragma("unroll") for (int k = 0; k < 2; ++k) \
;         acc[ai][bj][m][n] = __builtin_amdgcn_mfma_f32_16x16x32_bf16(Bt[n][k], At[m][k], acc[ai][bj][m][n], 0, 0, 0); __builtin_amdgcn_s_setprio(0); } while (0)
; #define PG8_WAIT_V(n) asm volatile("s_waitcnt vmcnt(" #n ")" ::: "memory")
; #define PG8_WAIT_L(n) asm volatile("s_waitcnt lgkmcnt(" #n ")" ::: "memory")
; #define PG8_BAR __builtin_amdgcn_s_barrier()
; #define PG8_SCHED __builtin_amdgcn_sched_barrier(0)
; template <class Epi, class Sched, bool ALIGN_EPI = false, bool SP2 = false>
; __device__ __forceinline__ void gemm_phase(PG8_LAS unsigned char* lds, const Gemm g, const Sched& S, const Epi& E) {
;     ...
;             PG8_LDA(At, 1, 1); PG8_STAGE(PG8_SB(1, 0), b3, voffB); PG8_STAGE(PG8_SB(1, 1), b3 + hstep, voffB); PG8_STAGE(PG8_SA(1, 0), a3, voffA);
;             PG8_WAIT_V(8); PG8_WAIT_L(0); PG8_BAR; PG8_MMA(1, 0, At, B0); PG8_MMA(1, 1, At, B1); PG8_BAR; PG8_SCHED;
;             } else {
;             PG8_LDB(B0, 0, 0); PG8_SCHED; PG8_LDA(At, 0, 0); PG8_STAGE(PG8_SA(1, 1), a1 + hstep, voffA);
	s_add_i32 s83, s81, s47
	s_add_i32 s35, s83, 0x2000
	v_lshl_add_u64 v[144:145], v[144:145], 0, s[22:23]
	s_mov_b32 m0, s83
	s_add_u32 s62, s62, 0x10180
	ds_read_b128 v[182:185], v151 offset:49152
	ds_read_b128 v[186:189], v151 offset:50176
	ds_read_b128 v[190:193], v151 offset:51200
	ds_read_b128 v[194:197], v151 offset:52224
	ds_read_b128 v[198:201], v151 offset:53248
	ds_read_b128 v[202:205], v151 offset:54272
	ds_read_b128 v[206:209], v151 offset:55296
	ds_read_b128 v[210:213], v151 offset:56320
	global_load_lds_dwordx4 v[144:145], off
	v_lshl_add_u64 v[144:145], v[214:215], 0, s[22:23]
	s_mov_b32 m0, s35
	s_addc_u32 s63, s63, 0
	s_add_i32 s37, s37, s47
	global_load_lds_dwordx4 v[144:145], off
	v_lshl_add_u64 v[144:145], s[62:63], 0, v[132:133]
	s_mov_b32 m0, s37
	s_nop 0
	global_load_lds_dwordx4 v[144:145], off
	v_lshl_add_u64 v[144:145], s[62:63], 0, v[128:129]
	s_add_i32 s62, s37, 0x2000
	s_mov_b32 m0, s62
	s_nop 0
	global_load_lds_dwordx4 v[144:145], off
	v_lshl_add_u64 v[144:145], v[216:217], 0, s[22:23]
	s_mov_b32 m0, s70
	s_nop 0
	global_load_lds_dwordx4 v[144:145], off
	v_lshl_add_u64 v[144:145], v[218:219], 0, s[22:23]
	s_mov_b32 m0, s71
	s_nop 0
	global_load_lds_dwordx4 v[144:145], off
	s_waitcnt vmcnt(8)
	s_waitcnt lgkmcnt(0)
	s_barrier
	s_setprio 1
	s_waitcnt lgkmcnt(0)
	v_mfma_f32_16x16x32_bf16 v[0:3], v[24:27], v[206:209], v[0:3]
	v_mfma_f32_16x16x32_bf16 v[4:7], v[112:115], v[206:209], v[4:7]
	v_mfma_f32_16x16x32_bf16 v[140:143], v[24:27], v[182:185], v[140:143]
	v_mfma_f32_16x16x32_bf16 v[154:157], v[112:115], v[182:185], v[154:157]
	v_mfma_f32_16x16x32_bf16 v[158:161], v[24:27], v[190:193], v[158:161]
	v_mfma_f32_16x16x32_bf16 v[162:165], v[112:115], v[190:193], v[162:165]
	v_mfma_f32_16x16x32_bf16 v[166:169], v[24:27], v[198:201], v[166:169]
	v_mfma_f32_16x16x32_bf16 v[170:173], v[112:115], v[198:201], v[170:173]
	v_mfma_f32_16x16x32_bf16 v[0:3], v[28:31], v[210:213], v[0:3]
	v_mfma_f32_16x16x32_bf16 v[4:7], v[116:119], v[210:213], v[4:7]
	v_mfma_f32_16x16x32_bf16 v[140:143], v[28:31], v[186:189], v[140:143]
	v_mfma_f32_16x16x32_bf16 v[154:157], v[116:119], v[186:189], v[154:157]
	v_mfma_f32_16x16x32_bf16 v[158:161], v[28:31], v[194:197], v[158:161]
	v_mfma_f32_16x16x32_bf16 v[162:165], v[116:119], v[194:197], v[162:165]
	v_mfma_f32_16x16x32_bf16 v[166:169], v[28:31], v[202:205], v[166:169]
	v_mfma_f32_16x16x32_bf16 v[170:173], v[116:119], v[202:205], v[170:173]
	s_setprio 0
	s_setprio 1
	v_mfma_f32_16x16x32_bf16 v[8:11], v[120:123], v[182:185], v[8:11]
	v_mfma_f32_16x16x32_bf16 v[12:15], v[174:177], v[182:185], v[12:15]
	v_mfma_f32_16x16x32_bf16 v[24:27], v[120:123], v[190:193], v[60:63]
	v_mfma_f32_16x16x32_bf16 v[28:31], v[174:177], v[190:193], v[100:103]
	v_mfma_f32_16x16x32_bf16 v[60:63], v[120:123], v[198:201], v[104:107]
	v_mfma_f32_16x16x32_bf16 v[100:103], v[174:177], v[198:201], v[108:111]
	v_mfma_f32_16x16x32_bf16 v[16:19], v[120:123], v[206:209], v[16:19]
	v_mfma_f32_16x16x32_bf16 v[20:23], v[174:177], v[206:209], v[20:23]
	v_mfma_f32_16x16x32_bf16 v[8:11], v[124:127], v[186:189], v[8:11]
	v_mfma_f32_16x16x32_bf16 v[12:15], v[178:181], v[186:189], v[12:15]
	v_mfma_f32_16x16x32_bf16 v[24:27], v[124:127], v[194:197], v[24:27]
	v_mfma_f32_16x16x32_bf16 v[28:31], v[178:181], v[194:197], v[28:31]
	v_mfma_f32_16x16x32_bf16 v[60:63], v[124:127], v[202:205], v[60:63]
	v_mfma_f32_16x16x32_bf16 v[100:103], v[178:181], v[202:205], v[100:103]
	v_mfma_f32_16x16x32_bf16 v[16:19], v[124:127], v[210:213], v[16:19]
	v_mfma_f32_16x16x32_bf16 v[20:23], v[178:181], v[210:213], v[20:23]
	s_setprio 0
	s_barrier
	ds_read_b128 v[104:107], v149
	ds_read_b128 v[108:111], v149 offset:1024
	ds_read_b128 v[112:115], v149 offset:2048
	ds_read_b128 v[116:119], v149 offset:3072
	ds_read_b128 v[120:123], v150
	ds_read_b128 v[124:127], v150 offset:1024
	ds_read_b128 v[174:177], v150 offset:2048
	ds_read_b128 v[178:181], v150 offset:3072
	s_add_u32 s52, s52, 0x10180
	s_addc_u32 s53, s53, 0
	s_mov_b32 m0, s73
	v_lshl_add_u64 v[144:145], s[52:53], 0, v[134:135]
	ds_read_b128 v[182:185], v151
	ds_read_b128 v[186:189], v151 offset:1024
	ds_read_b128 v[190:193], v151 offset:2048
	ds_read_b128 v[194:197], v151 offset:3072
	ds_read_b128 v[198:201], v151 offset:4096
	ds_read_b128 v[202:205], v151 offset:5120
	ds_read_b128 v[206:209], v151 offset:6144
	ds_read_b128 v[210:213], v151 offset:7168
	global_load_lds_dwordx4 v[144:145], off
	v_lshl_add_u64 v[144:145], s[52:53], 0, v[130:131]
	s_mov_b32 m0, s74
	s_nop 0
	global_load_lds_dwordx4 v[144:145], off
	s_waitcnt vmcnt(8)
	s_waitcnt lgkmcnt(0)
	s_barrier
; #define PG8_STAGE(bufoff, gbase, voff) do { _Pragma("unroll") for (int _i = 0; _i < 2; ++_i) \
;         __builtin_amdgcn_global_load_lds((const unsigned*)((const char*)(gbase) + (voff)[_i]), (PG8_LAS unsigned*)(lds + (bufoff) + ldsw + _i * 8192), 16, 0, 0); } while (0)
; #define PG8_LDA(dst, b, h) do { _Pragma("unroll") for (int m = 0; m < 4; ++m) _Pragma("unroll") for (int k = 0; k < 2; ++k) dst[m][k] = *(const PG8_LAS bf16x8*)(lds + PG8_SA(b, h) + aoff + m * 2048 + k * 1024); } while (0)
; #define PG8_MMA(ai, bj, At, Bt) do { __builtin_amdgcn_s_setprio(1); _Pragma("unroll") for (int m = 0; m < 4; ++m) _Pragma("unroll") for (int n = 0; n < 2; ++n) _Pragma("unroll") for (int k = 0; k < 2; ++k) \
;         acc[ai][bj][m][n] = __builtin_amdgcn_mfma_f32_16x16x32_bf16(Bt[n][k], At[m][k], acc[ai][bj][m][n], 0, 0, 0); __builtin_amdgcn_s_setprio(0); } while (0)
; #define PG8_WAIT_V(n) asm volatile("s_waitcnt vmcnt(" #n ")" ::: "memory")
; #define PG8_WAIT_L(n) asm volatile("s_waitcnt lgkmcnt(" #n ")" ::: "memory")
; #define PG8_BAR __builtin_amdgcn_s_barrier()
; #define PG8_SCHED __builtin_amdgcn_sched_barrier(0)
; template <class Epi, class Sched, bool ALIGN_EPI = false, bool SP2 = false>
; __device__ __forceinline__ void gemm_phase(PG8_LAS unsigned char* lds, const Gemm g, const Sched& S, const Epi& E) {
;     ...
;             PG8_WAIT_V(8); PG8_WAIT_L(0); PG8_BAR; PG8_MMA(0, 0, At, B0); PG8_MMA(0, 1, At, B1); PG8_BAR; PG8_SCHED;
;             PG8_LDA(At, 0, 1); PG8_STAGE(PG8_SB(0, 0), b2, voffB); PG8_STAGE(PG8_SB(0, 1), b2 + hstep, voffB); PG8_STAGE(PG8_SA(0, 0), a2, voffA);
;             PG8_WAIT_V(8); PG8_WAIT_L(0); PG8_BAR; PG8_MMA(1, 0, At, B0); PG8_MMA(1, 1, At, B1); PG8_BAR; PG8_SCHED;
	s_setprio 1
	s_waitcnt lgkmcnt(0)
	v_mfma_f32_16x16x32_bf16 v[64:67], v[104:107], v[182:185], v[64:67]
	v_mfma_f32_16x16x32_bf16 v[68:71], v[112:115], v[182:185], v[68:71]
	v_mfma_f32_16x16x32_bf16 v[72:75], v[104:107], v[190:193], v[72:75]
	v_mfma_f32_16x16x32_bf16 v[76:79], v[112:115], v[190:193], v[76:79]
	v_mfma_f32_16x16x32_bf16 v[80:83], v[104:107], v[198:201], v[80:83]
	v_mfma_f32_16x16x32_bf16 v[84:87], v[112:115], v[198:201], v[84:87]
	v_mfma_f32_16x16x32_bf16 v[88:91], v[104:107], v[206:209], v[88:91]
	v_mfma_f32_16x16x32_bf16 v[64:67], v[108:111], v[186:189], v[64:67]
	v_mfma_f32_16x16x32_bf16 v[68:71], v[116:119], v[186:189], v[68:71]
	v_mfma_f32_16x16x32_bf16 v[72:75], v[108:111], v[194:197], v[72:75]
	v_mfma_f32_16x16x32_bf16 v[76:79], v[116:119], v[194:197], v[76:79]
	v_mfma_f32_16x16x32_bf16 v[80:83], v[108:111], v[202:205], v[80:83]
	v_mfma_f32_16x16x32_bf16 v[84:87], v[116:119], v[202:205], v[84:87]
	v_mfma_f32_16x16x32_bf16 v[214:217], v[108:111], v[210:213], v[88:91]
	v_mfma_f32_16x16x32_bf16 v[88:91], v[112:115], v[206:209], v[92:95]
	v_mfma_f32_16x16x32_bf16 v[218:221], v[116:119], v[210:213], v[88:91]
	s_setprio 0
	s_setprio 1
	v_mfma_f32_16x16x32_bf16 v[88:91], v[120:123], v[182:185], v[96:99]
	v_mfma_f32_16x16x32_bf16 v[32:35], v[174:177], v[182:185], v[32:35]
	v_mfma_f32_16x16x32_bf16 v[36:39], v[120:123], v[190:193], v[36:39]
	v_mfma_f32_16x16x32_bf16 v[40:43], v[174:177], v[190:193], v[40:43]
	v_mfma_f32_16x16x32_bf16 v[44:47], v[120:123], v[198:201], v[44:47]
	v_mfma_f32_16x16x32_bf16 v[48:51], v[174:177], v[198:201], v[48:51]
	v_mfma_f32_16x16x32_bf16 v[52:55], v[120:123], v[206:209], v[52:55]
	v_mfma_f32_16x16x32_bf16 v[56:59], v[174:177], v[206:209], v[56:59]
	v_mfma_f32_16x16x32_bf16 v[96:99], v[124:127], v[186:189], v[88:91]
	v_mfma_f32_16x16x32_bf16 v[32:35], v[178:181], v[186:189], v[32:35]
	v_mfma_f32_16x16x32_bf16 v[36:39], v[124:127], v[194:197], v[36:39]
	v_mfma_f32_16x16x32_bf16 v[40:43], v[178:181], v[194:197], v[40:43]
	v_mfma_f32_16x16x32_bf16 v[44:47], v[124:127], v[202:205], v[44:47]
	v_mfma_f32_16x16x32_bf16 v[48:51], v[178:181], v[202:205], v[48:51]
	v_mfma_f32_16x16x32_bf16 v[52:55], v[124:127], v[210:213], v[52:55]
	v_mfma_f32_16x16x32_bf16 v[56:59], v[178:181], v[210:213], v[56:59]
	s_setprio 0
	s_barrier
	s_mov_b32 m0, s75
	v_lshl_add_u64 v[144:145], s[64:65], 0, v[132:133]
	s_add_u32 s52, s64, 0x10000
	ds_read_b128 v[88:91], v151 offset:16384
	ds_read_b128 v[92:95], v151 offset:17408
	ds_read_b128 v[182:185], v151 offset:18432
	ds_read_b128 v[186:189], v151 offset:19456
	ds_read_b128 v[190:193], v151 offset:20480
	ds_read_b128 v[194:197], v151 offset:21504
	ds_read_b128 v[198:201], v151 offset:22528
	ds_read_b128 v[202:205], v151 offset:23552
	global_load_lds_dwordx4 v[144:145], off
	v_lshl_add_u64 v[248:249], s[64:65], 0, v[128:129]
	s_mov_b32 m0, s76
	s_addc_u32 s53, s65, 0
	global_load_lds_dwordx4 v[248:249], off
	v_lshl_add_u64 v[206:207], s[52:53], 0, v[132:133]
	s_mov_b32 m0, s77
	v_lshl_add_u64 v[250:251], s[66:67], 0, v[134:135]
	global_load_lds_dwordx4 v[206:207], off
	v_lshl_add_u64 v[206:207], s[52:53], 0, v[128:129]
	s_mov_b32 m0, s80
	v_lshl_add_u64 v[252:253], s[66:67], 0, v[130:131]
	global_load_lds_dwordx4 v[206:207], off
	s_mov_b32 m0, s43
	s_nop 0
	global_load_lds_dwordx4 v[250:251], off
	s_mov_b32 m0, s61
	s_nop 0
	global_load_lds_dwordx4 v[252:253], off
	s_waitcnt vmcnt(8)
	s_waitcnt lgkmcnt(0)
	s_barrier
	s_setprio 1
	s_waitcnt lgkmcnt(0)
	v_mfma_f32_16x16x32_bf16 v[0:3], v[104:107], v[198:201], v[0:3]
	v_mfma_f32_16x16x32_bf16 v[4:7], v[112:115], v[198:201], v[4:7]
	v_mfma_f32_16x16x32_bf16 v[140:143], v[104:107], v[88:91], v[140:143]
	v_mfma_f32_16x16x32_bf16 v[154:157], v[112:115], v[88:91], v[154:157]
	v_mfma_f32_16x16x32_bf16 v[158:161], v[104:107], v[182:185], v[158:161]
	v_mfma_f32_16x16x32_bf16 v[162:165], v[112:115], v[182:185], v[162:165]
	v_mfma_f32_16x16x32_bf16 v[166:169], v[104:107], v[190:193], v[166:169]
	v_mfma_f32_16x16x32_bf16 v[170:173], v[112:115], v[190:193], v[170:173]
	v_mfma_f32_16x16x32_bf16 v[0:3], v[108:111], v[202:205], v[0:3]
	v_mfma_f32_16x16x32_bf16 v[4:7], v[116:119], v[202:205], v[4:7]
	v_mfma_f32_16x16x32_bf16 v[140:143], v[108:111], v[92:95], v[140:143]
	v_mfma_f32_16x16x32_bf16 v[154:157], v[116:119], v[92:95], v[154:157]
	v_mfma_f32_16x16x32_bf16 v[158:161], v[108:111], v[186:189], v[158:161]
	v_mfma_f32_16x16x32_bf16 v[162:165], v[116:119], v[186:189], v[162:165]
	v_mfma_f32_16x16x32_bf16 v[166:169], v[108:111], v[194:197], v[166:169]
	v_mfma_f32_16x16x32_bf16 v[170:173], v[116:119], v[194:197], v[170:173]
	s_setprio 0
	s_setprio 1
	v_mfma_f32_16x16x32_bf16 v[8:11], v[120:123], v[88:91], v[8:11]
	v_mfma_f32_16x16x32_bf16 v[206:209], v[124:127], v[92:95], v[8:11]
	v_mfma_f32_16x16x32_bf16 v[8:11], v[174:177], v[88:91], v[12:15]
	v_mfma_f32_16x16x32_bf16 v[210:213], v[178:181], v[92:95], v[8:11]
	v_mfma_f32_16x16x32_bf16 v[8:11], v[120:123], v[182:185], v[24:27]
	v_mfma_f32_16x16x32_bf16 v[222:225], v[124:127], v[186:189], v[8:11]
	v_mfma_f32_16x16x32_bf16 v[8:11], v[174:177], v[182:185], v[28:31]
	v_mfma_f32_16x16x32_bf16 v[182:185], v[178:181], v[186:189], v[8:11]
	v_mfma_f32_16x16x32_bf16 v[8:11], v[120:123], v[190:193], v[60:63]
	v_mfma_f32_16x16x32_bf16 v[186:189], v[124:127], v[194:197], v[8:11]
	v_mfma_f32_16x16x32_bf16 v[8:11], v[174:177], v[190:193], v[100:103]
	v_mfma_f32_16x16x32_bf16 v[190:193], v[178:181], v[194:197], v[8:11]
	v_mfma_f32_16x16x32_bf16 v[8:11], v[120:123], v[198:201], v[16:19]
	v_mfma_f32_16x16x32_bf16 v[194:197], v[124:127], v[202:205], v[8:11]
	v_mfma_f32_16x16x32_bf16 v[8:11], v[174:177], v[198:201], v[20:23]
	v_mfma_f32_16x16x32_bf16 v[174:177], v[178:181], v[202:205], v[8:11]
	s_setprio 0
	s_barrier
; #define PG8_STAGE(bufoff, gbase, voff) do { _Pragma("unroll") for (int _i = 0; _i < 2; ++_i) \
;         __builtin_amdgcn_global_load_lds((const unsigned*)((const char*)(gbase) + (voff)[_i]), (PG8_LAS unsigned*)(lds + (bufoff) + ldsw + _i * 8192), 16, 0, 0); } while (0)
; #define PG8_LDA(dst, b, h) do { _Pragma("unroll") for (int m = 0; m < 4; ++m) _Pragma("unroll") for (int k = 0; k < 2; ++k) dst[m][k] = *(const PG8_LAS bf16x8*)(lds + PG8_SA(b, h) + aoff + m * 2048 + k * 1024); } while (0)
; #define PG8_LDB(dst, b, h) do { _Pragma("unroll") for (int n = 0; n < 2; ++n) _Pragma("unroll") for (int k = 0; k < 2; ++k) dst[n][k] = *(const PG8_LAS bf16x8*)(lds + PG8_SB(b, h) + boff + n * 2048 + k * 1024); } while (0)
; #define PG8_MMA(ai, bj, At, Bt) do { __builtin_amdgcn_s_setprio(1); _Pragma("unroll") for (int m = 0; m < 4; ++m) _Pragma("unroll") for (int n = 0; n < 2; ++n) _Pragma("unroll") for (int k = 0; k < 2; ++k) \
;         acc[ai][bj][m][n] = __builtin_amdgcn_mfma_f32_16x16x32_bf16(Bt[n][k], At[m][k], acc[ai][bj][m][n], 0, 0, 0); __builtin_amdgcn_s_setprio(0); } while (0)
; #define PG8_WAIT_V(n) asm volatile("s_waitcnt vmcnt(" #n ")" ::: "memory")
; #define PG8_WAIT_L(n) asm volatile("s_waitcnt lgkmcnt(" #n ")" ::: "memory")
; #define PG8_BAR __builtin_amdgcn_s_barrier()
; #define PG8_SCHED __builtin_amdgcn_sched_barrier(0)
; template <class Epi, class Sched, bool ALIGN_EPI = false, bool SP2 = false>
; __device__ __forceinline__ void gemm_phase(PG8_LAS unsigned char* lds, const Gemm g, const Sched& S, const Epi& E) {
;     ...
;             PG8_LDB(B0, 1, 0); PG8_LDB(B1, 1, 1); PG8_SCHED; PG8_LDA(At, 1, 0); PG8_STAGE(PG8_SA(0, 1), a2 + hstep, voffA);
;             PG8_WAIT_V(8); PG8_WAIT_L(0); PG8_BAR; PG8_MMA(0, 0, At, B0); PG8_MMA(0, 1, At, B1); PG8_BAR; PG8_SCHED;
;             PG8_LDA(At, 1, 1); PG8_STAGE(PG8_SB(1, 0), b3, voffB); PG8_STAGE(PG8_SB(1, 1), b3 + hstep, voffB); PG8_STAGE(PG8_SA(1, 0), a3, voffA);
;             PG8_WAIT_V(8); PG8_WAIT_L(0); PG8_BAR; PG8_MMA(1, 0, At, B0); PG8_MMA(1, 1, At, B1); PG8_BAR; PG8_SCHED;
	s_nop 4
	ds_read_b128 v[8:11], v152
	ds_read_b128 v[12:15], v152 offset:1024
	ds_read_b128 v[16:19], v152 offset:2048
	ds_read_b128 v[20:23], v152 offset:3072
	ds_read_b128 v[178:181], v153
	ds_read_b128 v[198:201], v153 offset:1024
	ds_read_b128 v[202:205], v153 offset:2048
	ds_read_b128 v[228:231], v153 offset:3072
	s_add_u32 s52, s66, 0x10000
	s_addc_u32 s53, s67, 0
	s_mov_b32 m0, s68
	v_lshl_add_u64 v[88:89], s[52:53], 0, v[134:135]
	ds_read_b128 v[24:27], v151 offset:32768
	ds_read_b128 v[28:31], v151 offset:33792
	ds_read_b128 v[60:63], v151 offset:34816
	ds_read_b128 v[100:103], v151 offset:35840
	ds_read_b128 v[232:235], v151 offset:36864
	ds_read_b128 v[236:239], v151 offset:37888
	ds_read_b128 v[240:243], v151 offset:38912
	ds_read_b128 v[244:247], v151 offset:39936
	global_load_lds_dwordx4 v[88:89], off
	v_lshl_add_u64 v[88:89], s[52:53], 0, v[130:131]
	s_mov_b32 m0, s69
	s_nop 0
	global_load_lds_dwordx4 v[88:89], off
	s_waitcnt vmcnt(8)
	s_waitcnt lgkmcnt(0)
	s_barrier
	s_setprio 1
	s_waitcnt lgkmcnt(0)
	v_mfma_f32_16x16x32_bf16 v[64:67], v[8:11], v[24:27], v[64:67]
	v_mfma_f32_16x16x32_bf16 v[124:127], v[12:15], v[28:31], v[64:67]
	v_mfma_f32_16x16x32_bf16 v[64:67], v[16:19], v[24:27], v[68:71]
	v_mfma_f32_16x16x32_bf16 v[120:123], v[20:23], v[28:31], v[64:67]
	v_mfma_f32_16x16x32_bf16 v[64:67], v[8:11], v[60:63], v[72:75]
	v_mfma_f32_16x16x32_bf16 v[108:111], v[12:15], v[100:103], v[64:67]
	v_mfma_f32_16x16x32_bf16 v[64:67], v[16:19], v[60:63], v[76:79]
	v_mfma_f32_16x16x32_bf16 v[104:107], v[20:23], v[100:103], v[64:67]
	v_mfma_f32_16x16x32_bf16 v[64:67], v[8:11], v[232:235], v[80:83]
	v_mfma_f32_16x16x32_bf16 v[92:95], v[12:15], v[236:239], v[64:67]
	v_mfma_f32_16x16x32_bf16 v[64:67], v[16:19], v[232:235], v[84:87]
	v_mfma_f32_16x16x32_bf16 v[88:91], v[20:23], v[236:239], v[64:67]
	v_mfma_f32_16x16x32_bf16 v[64:67], v[8:11], v[240:243], v[214:217]
	v_mfma_f32_16x16x32_bf16 v[76:79], v[12:15], v[244:247], v[64:67]
	v_mfma_f32_16x16x32_bf16 v[64:67], v[16:19], v[240:243], v[218:221]
	v_mfma_f32_16x16x32_bf16 v[72:75], v[20:23], v[244:247], v[64:67]
	s_setprio 0
	s_setprio 1
	v_mfma_f32_16x16x32_bf16 v[64:67], v[178:181], v[24:27], v[96:99]
	v_mfma_f32_16x16x32_bf16 v[24:27], v[202:205], v[24:27], v[32:35]
	v_mfma_f32_16x16x32_bf16 v[116:119], v[228:231], v[28:31], v[24:27]
	v_mfma_f32_16x16x32_bf16 v[24:27], v[178:181], v[60:63], v[36:39]
	v_mfma_f32_16x16x32_bf16 v[96:99], v[198:201], v[100:103], v[24:27]
	v_mfma_f32_16x16x32_bf16 v[24:27], v[202:205], v[60:63], v[40:43]
	v_mfma_f32_16x16x32_bf16 v[100:103], v[228:231], v[100:103], v[24:27]
	v_mfma_f32_16x16x32_bf16 v[24:27], v[178:181], v[232:235], v[44:47]
	v_mfma_f32_16x16x32_bf16 v[80:83], v[198:201], v[236:239], v[24:27]
	v_mfma_f32_16x16x32_bf16 v[24:27], v[202:205], v[232:235], v[48:51]
	v_mfma_f32_16x16x32_bf16 v[84:87], v[228:231], v[236:239], v[24:27]
	v_mfma_f32_16x16x32_bf16 v[24:27], v[178:181], v[240:243], v[52:55]
	v_mfma_f32_16x16x32_bf16 v[112:115], v[198:201], v[28:31], v[64:67]
	v_mfma_f32_16x16x32_bf16 v[64:67], v[198:201], v[244:247], v[24:27]
	v_mfma_f32_16x16x32_bf16 v[24:27], v[202:205], v[240:243], v[56:59]
	v_mfma_f32_16x16x32_bf16 v[68:71], v[228:231], v[244:247], v[24:27]
	s_setprio 0
	s_barrier
	s_mov_b32 m0, s83
	s_nop 3
	v_lshl_add_u64 v[24:25], v[144:145], 0, s[14:15]
	s_add_u32 s52, s64, 0x10080
	ds_read_b128 v[32:35], v151 offset:49152
	ds_read_b128 v[36:39], v151 offset:50176
	ds_read_b128 v[214:217], v151 offset:51200
	ds_read_b128 v[218:221], v151 offset:52224
	ds_read_b128 v[232:235], v151 offset:53248
	ds_read_b128 v[236:239], v151 offset:54272
	ds_read_b128 v[240:243], v151 offset:55296
	ds_read_b128 v[244:247], v151 offset:56320
	global_load_lds_dwordx4 v[24:25], off
	v_lshl_add_u64 v[24:25], v[248:249], 0, s[14:15]
	s_mov_b32 m0, s35
	s_addc_u32 s53, s65, 0
	global_load_lds_dwordx4 v[24:25], off
	v_lshl_add_u64 v[24:25], s[52:53], 0, v[132:133]
	s_mov_b32 m0, s37
	s_nop 0
	global_load_lds_dwordx4 v[24:25], off
	v_lshl_add_u64 v[24:25], s[52:53], 0, v[128:129]
	s_mov_b32 m0, s62
	s_nop 0
	global_load_lds_dwordx4 v[24:25], off
	v_lshl_add_u64 v[24:25], v[250:251], 0, s[14:15]
	s_mov_b32 m0, s70
	s_nop 0
	global_load_lds_dwordx4 v[24:25], off
	v_lshl_add_u64 v[24:25], v[252:253], 0, s[14:15]
	s_mov_b32 m0, s71
	s_nop 0
	global_load_lds_dwordx4 v[24:25], off
	s_waitcnt vmcnt(8)
	s_waitcnt lgkmcnt(0)
	s_barrier
	s_setprio 1
	s_waitcnt lgkmcnt(0)
	v_mfma_f32_16x16x32_bf16 v[24:27], v[8:11], v[32:35], v[140:143]
	v_mfma_f32_16x16x32_bf16 v[60:63], v[12:15], v[36:39], v[24:27]
	v_mfma_f32_16x16x32_bf16 v[24:27], v[16:19], v[32:35], v[154:157]
	v_mfma_f32_16x16x32_bf16 v[56:59], v[20:23], v[36:39], v[24:27]
	v_mfma_f32_16x16x32_bf16 v[24:27], v[8:11], v[214:217], v[158:161]
	v_mfma_f32_16x16x32_bf16 v[44:47], v[12:15], v[218:221], v[24:27]
	v_mfma_f32_16x16x32_bf16 v[24:27], v[16:19], v[214:217], v[162:165]
	v_mfma_f32_16x16x32_bf16 v[40:43], v[20:23], v[218:221], v[24:27]
	v_mfma_f32_16x16x32_bf16 v[24:27], v[8:11], v[232:235], v[166:169]
	v_mfma_f32_16x16x32_bf16 v[0:3], v[8:11], v[240:243], v[0:3]
	v_mfma_f32_16x16x32_bf16 v[28:31], v[12:15], v[236:239], v[24:27]
	v_mfma_f32_16x16x32_bf16 v[24:27], v[16:19], v[232:235], v[170:173]
	v_mfma_f32_16x16x32_bf16 v[12:15], v[12:15], v[244:247], v[0:3]
	v_mfma_f32_16x16x32_bf16 v[0:3], v[16:19], v[240:243], v[4:7]
	v_mfma_f32_16x16x32_bf16 v[24:27], v[20:23], v[236:239], v[24:27]
	v_mfma_f32_16x16x32_bf16 v[8:11], v[20:23], v[244:247], v[0:3]
	s_setprio 0
	s_setprio 1
	v_mfma_f32_16x16x32_bf16 v[0:3], v[178:181], v[32:35], v[206:209]
	v_mfma_f32_16x16x32_bf16 v[48:51], v[198:201], v[36:39], v[0:3]
	v_mfma_f32_16x16x32_bf16 v[0:3], v[202:205], v[32:35], v[210:213]
	v_mfma_f32_16x16x32_bf16 v[52:55], v[228:231], v[36:39], v[0:3]
	v_mfma_f32_16x16x32_bf16 v[0:3], v[178:181], v[214:217], v[222:225]
	v_mfma_f32_16x16x32_bf16 v[32:35], v[198:201], v[218:221], v[0:3]
	v_mfma_f32_16x16x32_bf16 v[0:3], v[202:205], v[214:217], v[182:185]
	v_mfma_f32_16x16x32_bf16 v[36:39], v[228:231], v[218:221], v[0:3]
	v_mfma_f32_16x16x32_bf16 v[0:3], v[178:181], v[232:235], v[186:189]
	v_mfma_f32_16x16x32_bf16 v[16:19], v[198:201], v[236:239], v[0:3]
	v_mfma_f32_16x16x32_bf16 v[0:3], v[202:205], v[232:235], v[190:193]
	v_mfma_f32_16x16x32_bf16 v[20:23], v[228:231], v[236:239], v[0:3]
	v_mfma_f32_16x16x32_bf16 v[0:3], v[178:181], v[240:243], v[194:197]
	v_mfma_f32_16x16x32_bf16 v[4:7], v[198:201], v[244:247], v[0:3]
	v_mfma_f32_16x16x32_bf16 v[0:3], v[202:205], v[240:243], v[174:177]
	v_mfma_f32_16x16x32_bf16 v[0:3], v[228:231], v[244:247], v[0:3]
	s_setprio 0
	s_barrier
; __device__ __forceinline__ u32x4 pack8(const f32x4 a, const f32x4 b) { u32x4 w; w.x = cvt_pk_bf16(a[0], a[1]); w.y = cvt_pk_bf16(a[2], a[3]); w.z = cvt_pk_bf16(b[0], b[1]); w.w = cvt_pk_bf16(b[2], b[3]); return w; }
; __device__ __forceinline__ void unpack8(const u32x4 w, f32x4& a, f32x4& b) { a = (f32x4){bflo(w.x), bfhi(w.x), bflo(w.y), bfhi(w.y)}; b = (f32x4){bflo(w.z), bfhi(w.z), bflo(w.w), bfhi(w.w)}; }
;     __device__ __forceinline__ void operator()(const f32x4 (&acc)[2][2][4][2], const Unit& u, int wr, int wc, int fr, int fq) const {
;         const int rbase = u.pm * 256 + wr * 64 + fr, cb = u.pn * 256 + wc * 32 + fq * 8;
; #pragma unroll
;         for (int ai = 0; ai < 2; ++ai)
; #pragma unroll
;             for (int m = 0; m < 4; ++m) { const size_t ro = (size_t)(rbase + ai * 128 + m * 16) * 1024 + cb;
; #pragma unroll
;                 for (int bj = 0; bj < 2; ++bj) { f32x4 g0, g1; unpack8(*(const u32x4*)(G + ro + bj * 128), g0, g1);
;                     f32x4 v0 = acc[ai][bj][m][0] * g0, v1 = acc[ai][bj][m][1] * g1;
;                     if (!FIRST) { f32x4 o0, o1; unpack8(*(const u32x4*)(O + ro + bj * 128), o0, o1); v0 += o0; v1 += o1; }
;                     *(u32x4*)(O + ro + bj * 128) = pack8(v0, v1); }
;                 asm volatile("" ::: "memory"); }
	v_lshl_add_u32 v144, s42, 8, v146
	v_lshl_or_b32 v142, s82, 8, v148
	v_lshlrev_b32_e32 v140, 11, v144
	v_lshl_add_u32 v140, v142, 1, v140
	v_mov_b32_e32 v141, v140
	global_load_dwordx4 v[154:157], v141, s[12:13]
	global_load_dwordx4 v[158:161], v141, s[12:13] offset:256
	global_load_dwordx4 v[162:165], v141, s[8:9]
	global_load_dwordx4 v[166:169], v141, s[8:9] offset:256
	v_add_u32_e32 v141, 0x8000, v140
	global_load_dwordx4 v[170:173], v141, s[12:13]
	global_load_dwordx4 v[174:177], v141, s[12:13] offset:256
	global_load_dwordx4 v[178:181], v141, s[8:9]
	global_load_dwordx4 v[182:185], v141, s[8:9] offset:256
	v_add_u32_e32 v141, 0x10000, v140
	global_load_dwordx4 v[186:189], v141, s[12:13]
	global_load_dwordx4 v[190:193], v141, s[12:13] offset:256
	global_load_dwordx4 v[194:197], v141, s[8:9]
	global_load_dwordx4 v[198:201], v141, s[8:9] offset:256
	v_add_u32_e32 v141, 0x18000, v140
	global_load_dwordx4 v[202:205], v141, s[12:13]
	global_load_dwordx4 v[206:209], v141, s[12:13] offset:256
	global_load_dwordx4 v[210:213], v141, s[8:9]
	global_load_dwordx4 v[214:217], v141, s[8:9] offset:256
	s_andn2_b64 vcc, exec, s[16:17]
	s_cbranch_vccnz .LBB0_1356
	s_barrier
.LBB0_1356:
	s_waitcnt vmcnt(12)
	v_mov_b32_e32 v143, v140
	v_lshlrev_b32_e32 v228, 16, v154
	v_and_b32_e32 v229, 0xffff0000, v154
	v_lshlrev_b32_e32 v236, 16, v162
	v_and_b32_e32 v237, 0xffff0000, v162
	v_lshlrev_b32_e32 v230, 16, v155
	v_and_b32_e32 v231, 0xffff0000, v155
	v_lshlrev_b32_e32 v238, 16, v163
	v_and_b32_e32 v239, 0xffff0000, v163
	v_lshlrev_b32_e32 v232, 16, v156
	v_and_b32_e32 v233, 0xffff0000, v156
	v_lshlrev_b32_e32 v240, 16, v164
	v_and_b32_e32 v241, 0xffff0000, v164
	v_lshlrev_b32_e32 v234, 16, v157
	v_and_b32_e32 v235, 0xffff0000, v157
	v_lshlrev_b32_e32 v242, 16, v165
	v_and_b32_e32 v243, 0xffff0000, v165
	v_pk_fma_f32 v[124:125], v[124:125], v[228:229], v[236:237]
	v_pk_fma_f32 v[126:127], v[126:127], v[230:231], v[238:239]
	v_pk_fma_f32 v[120:121], v[120:121], v[232:233], v[240:241]
	v_pk_fma_f32 v[122:123], v[122:123], v[234:235], v[242:243]
	v_cvt_pk_bf16_f32 v154, v124, v125
	v_cvt_pk_bf16_f32 v155, v126, v127
	v_cvt_pk_bf16_f32 v156, v120, v121
	v_cvt_pk_bf16_f32 v157, v122, v123
	global_store_dwordx4 v143, v[154:157], s[8:9]
	v_lshlrev_b32_e32 v228, 16, v158
	v_and_b32_e32 v229, 0xffff0000, v158
	v_lshlrev_b32_e32 v236, 16, v166
	v_and_b32_e32 v237, 0xffff0000, v166
	v_lshlrev_b32_e32 v230, 16, v159
	v_and_b32_e32 v231, 0xffff0000, v159
	v_lshlrev_b32_e32 v238, 16, v167
	v_and_b32_e32 v239, 0xffff0000, v167
	v_lshlrev_b32_e32 v232, 16, v160
	v_and_b32_e32 v233, 0xffff0000, v160
	v_lshlrev_b32_e32 v240, 16, v168
	v_and_b32_e32 v241, 0xffff0000, v168
	v_lshlrev_b32_e32 v234, 16, v161
	v_and_b32_e32 v235, 0xffff0000, v161
	v_lshlrev_b32_e32 v242, 16, v169
	v_and_b32_e32 v243, 0xffff0000, v169
	v_pk_fma_f32 v[112:113], v[112:113], v[228:229], v[236:237]
	v_pk_fma_f32 v[114:115], v[114:115], v[230:231], v[238:239]
	v_pk_fma_f32 v[116:117], v[116:117], v[232:233], v[240:241]
	v_pk_fma_f32 v[118:119], v[118:119], v[234:235], v[242:243]
	v_cvt_pk_bf16_f32 v158, v112, v113
	v_cvt_pk_bf16_f32 v159, v114, v115
	v_cvt_pk_bf16_f32 v160, v116, v117
	v_cvt_pk_bf16_f32 v161, v118, v119
	global_store_dwordx4 v143, v[158:161], s[8:9] offset:256
	v_add_u32_e32 v141, 0x40000, v140
	global_load_dwordx4 v[154:157], v141, s[12:13]
	global_load_dwordx4 v[158:161], v141, s[12:13] offset:256
	global_load_dwordx4 v[162:165], v141, s[8:9]
	global_load_dwordx4 v[166:169], v141, s[8:9] offset:256
	s_waitcnt vmcnt(14)
	v_add_u32_e32 v143, 0x8000, v140
	v_lshlrev_b32_e32 v228, 16, v170
	v_and_b32_e32 v229, 0xffff0000, v170
	v_lshlrev_b32_e32 v236, 16, v178
	v_and_b32_e32 v237, 0xffff0000, v178
	v_lshlrev_b32_e32 v230, 16, v171
	v_and_b32_e32 v231, 0xffff0000, v171
	v_lshlrev_b32_e32 v238, 16, v179
	v_and_b32_e32 v239, 0xffff0000, v179
	v_lshlrev_b32_e32 v232, 16, v172
	v_and_b32_e32 v233, 0xffff0000, v172
	v_lshlrev_b32_e32 v240, 16, v180
	v_and_b32_e32 v241, 0xffff0000, v180
	v_lshlrev_b32_e32 v234, 16, v173
	v_and_b32_e32 v235, 0xffff0000, v173
	v_lshlrev_b32_e32 v242, 16, v181
	v_and_b32_e32 v243, 0xffff0000, v181
	v_pk_fma_f32 v[108:109], v[108:109], v[228:229], v[236:237]
	v_pk_fma_f32 v[110:111], v[110:111], v[230:231], v[238:239]
	v_pk_fma_f32 v[104:105], v[104:105], v[232:233], v[240:241]
	v_pk_fma_f32 v[106:107], v[106:107], v[234:235], v[242:243]
	v_cvt_pk_bf16_f32 v170, v108, v109
	v_cvt_pk_bf16_f32 v171, v110, v111
	v_cvt_pk_bf16_f32 v172, v104, v105
	v_cvt_pk_bf16_f32 v173, v106, v107
	global_store_dwordx4 v143, v[170:173], s[8:9]
	v_lshlrev_b32_e32 v228, 16, v174
	v_and_b32_e32 v229, 0xffff0000, v174
	v_lshlrev_b32_e32 v236, 16, v182
	v_and_b32_e32 v237, 0xffff0000, v182
	v_lshlrev_b32_e32 v230, 16, v175
	v_and_b32_e32 v231, 0xffff0000, v175
	v_lshlrev_b32_e32 v238, 16, v183
	v_and_b32_e32 v239, 0xffff0000, v183
	v_lshlrev_b32_e32 v232, 16, v176
	v_and_b32_e32 v233, 0xffff0000, v176
	v_lshlrev_b32_e32 v240, 16, v184
	v_and_b32_e32 v241, 0xffff0000, v184
	v_lshlrev_b32_e32 v234, 16, v177
	v_and_b32_e32 v235, 0xffff0000, v177
	v_lshlrev_b32_e32 v242, 16, v185
	v_and_b32_e32 v243, 0xffff0000, v185
	v_pk_fma_f32 v[96:97], v[96:97], v[228:229], v[236:237]
	v_pk_fma_f32 v[98:99], v[98:99], v[230:231], v[238:239]
	v_pk_fma_f32 v[100:101], v[100:101], v[232:233], v[240:241]
	v_pk_fma_f32 v[102:103], v[102:103], v[234:235], v[242:243]
	v_cvt_pk_bf16_f32 v174, v96, v97
	v_cvt_pk_bf16_f32 v175, v98, v99
	v_cvt_pk_bf16_f32 v176, v100, v101
	v_cvt_pk_bf16_f32 v177, v102, v103
	global_store_dwordx4 v143, v[174:177], s[8:9] offset:256
	v_add_u32_e32 v141, 0x48000, v140
	global_load_dwordx4 v[170:173], v141, s[12:13]
	global_load_dwordx4 v[174:177], v141, s[12:13] offset:256
	global_load_dwordx4 v[178:181], v141, s[8:9]
	global_load_dwordx4 v[182:185], v141, s[8:9] offset:256
	s_waitcnt vmcnt(16)
; __device__ __forceinline__ u32x4 pack8(const f32x4 a, const f32x4 b) { u32x4 w; w.x = cvt_pk_bf16(a[0], a[1]); w.y = cvt_pk_bf16(a[2], a[3]); w.z = cvt_pk_bf16(b[0], b[1]); w.w = cvt_pk_bf16(b[2], b[3]); return w; }
; __device__ __forceinline__ void unpack8(const u32x4 w, f32x4& a, f32x4& b) { a = (f32x4){bflo(w.x), bfhi(w.x), bflo(w.y), bfhi(w.y)}; b = (f32x4){bflo(w.z), bfhi(w.z), bflo(w.w), bfhi(w.w)}; }
;     __device__ __forceinline__ void operator()(const f32x4 (&acc)[2][2][4][2], const Unit& u, int wr, int wc, int fr, int fq) const {
;         const int rbase = u.pm * 256 + wr * 64 + fr, cb = u.pn * 256 + wc * 32 + fq * 8;
; #pragma unroll
;         for (int ai = 0; ai < 2; ++ai)
; #pragma unroll
;             for (int m = 0; m < 4; ++m) { const size_t ro = (size_t)(rbase + ai * 128 + m * 16) * 1024 + cb;
; #pragma unroll
;                 for (int bj = 0; bj < 2; ++bj) { f32x4 g0, g1; unpack8(*(const u32x4*)(G + ro + bj * 128), g0, g1);
;                     f32x4 v0 = acc[ai][bj][m][0] * g0, v1 = acc[ai][bj][m][1] * g1;
;                     if (!FIRST) { f32x4 o0, o1; unpack8(*(const u32x4*)(O + ro + bj * 128), o0, o1); v0 += o0; v1 += o1; }
;                     *(u32x4*)(O + ro + bj * 128) = pack8(v0, v1); }
;                 asm volatile("" ::: "memory"); }
	v_add_u32_e32 v143, 0x10000, v140
	v_lshlrev_b32_e32 v228, 16, v186
	v_and_b32_e32 v229, 0xffff0000, v186
	v_lshlrev_b32_e32 v236, 16, v194
	v_and_b32_e32 v237, 0xffff0000, v194
	v_lshlrev_b32_e32 v230, 16, v187
	v_and_b32_e32 v231, 0xffff0000, v187
	v_lshlrev_b32_e32 v238, 16, v195
	v_and_b32_e32 v239, 0xffff0000, v195
	v_lshlrev_b32_e32 v232, 16, v188
	v_and_b32_e32 v233, 0xffff0000, v188
	v_lshlrev_b32_e32 v240, 16, v196
	v_and_b32_e32 v241, 0xffff0000, v196
	v_lshlrev_b32_e32 v234, 16, v189
	v_and_b32_e32 v235, 0xffff0000, v189
	v_lshlrev_b32_e32 v242, 16, v197
	v_and_b32_e32 v243, 0xffff0000, v197
	v_pk_fma_f32 v[92:93], v[92:93], v[228:229], v[236:237]
	v_pk_fma_f32 v[94:95], v[94:95], v[230:231], v[238:239]
	v_pk_fma_f32 v[88:89], v[88:89], v[232:233], v[240:241]
	v_pk_fma_f32 v[90:91], v[90:91], v[234:235], v[242:243]
	v_cvt_pk_bf16_f32 v186, v92, v93
	v_cvt_pk_bf16_f32 v187, v94, v95
	v_cvt_pk_bf16_f32 v188, v88, v89
	v_cvt_pk_bf16_f32 v189, v90, v91
	global_store_dwordx4 v143, v[186:189], s[8:9]
	v_lshlrev_b32_e32 v228, 16, v190
	v_and_b32_e32 v229, 0xffff0000, v190
	v_lshlrev_b32_e32 v236, 16, v198
	v_and_b32_e32 v237, 0xffff0000, v198
	v_lshlrev_b32_e32 v230, 16, v191
	v_and_b32_e32 v231, 0xffff0000, v191
	v_lshlrev_b32_e32 v238, 16, v199
	v_and_b32_e32 v239, 0xffff0000, v199
	v_lshlrev_b32_e32 v232, 16, v192
	v_and_b32_e32 v233, 0xffff0000, v192
	v_lshlrev_b32_e32 v240, 16, v200
	v_and_b32_e32 v241, 0xffff0000, v200
	v_lshlrev_b32_e32 v234, 16, v193
	v_and_b32_e32 v235, 0xffff0000, v193
	v_lshlrev_b32_e32 v242, 16, v201
	v_and_b32_e32 v243, 0xffff0000, v201
	v_pk_fma_f32 v[80:81], v[80:81], v[228:229], v[236:237]
	v_pk_fma_f32 v[82:83], v[82:83], v[230:231], v[238:239]
	v_pk_fma_f32 v[84:85], v[84:85], v[232:233], v[240:241]
	v_pk_fma_f32 v[86:87], v[86:87], v[234:235], v[242:243]
	v_cvt_pk_bf16_f32 v190, v80, v81
	v_cvt_pk_bf16_f32 v191, v82, v83
	v_cvt_pk_bf16_f32 v192, v84, v85
	v_cvt_pk_bf16_f32 v193, v86, v87
	global_store_dwordx4 v143, v[190:193], s[8:9] offset:256
	v_add_u32_e32 v141, 0x50000, v140
	global_load_dwordx4 v[186:189], v141, s[12:13]
	global_load_dwordx4 v[190:193], v141, s[12:13] offset:256
	global_load_dwordx4 v[194:197], v141, s[8:9]
	global_load_dwordx4 v[198:201], v141, s[8:9] offset:256
	s_waitcnt vmcnt(18)
	v_add_u32_e32 v143, 0x18000, v140
	v_lshlrev_b32_e32 v228, 16, v202
	v_and_b32_e32 v229, 0xffff0000, v202
	v_lshlrev_b32_e32 v236, 16, v210
	v_and_b32_e32 v237, 0xffff0000, v210
	v_lshlrev_b32_e32 v230, 16, v203
	v_and_b32_e32 v231, 0xffff0000, v203
	v_lshlrev_b32_e32 v238, 16, v211
	v_and_b32_e32 v239, 0xffff0000, v211
	v_lshlrev_b32_e32 v232, 16, v204
	v_and_b32_e32 v233, 0xffff0000, v204
	v_lshlrev_b32_e32 v240, 16, v212
	v_and_b32_e32 v241, 0xffff0000, v212
	v_lshlrev_b32_e32 v234, 16, v205
	v_and_b32_e32 v235, 0xffff0000, v205
	v_lshlrev_b32_e32 v242, 16, v213
	v_and_b32_e32 v243, 0xffff0000, v213
	v_pk_fma_f32 v[76:77], v[76:77], v[228:229], v[236:237]
	v_pk_fma_f32 v[78:79], v[78:79], v[230:231], v[238:239]
	v_pk_fma_f32 v[72:73], v[72:73], v[232:233], v[240:241]
	v_pk_fma_f32 v[74:75], v[74:75], v[234:235], v[242:243]
	v_cvt_pk_bf16_f32 v202, v76, v77
	v_cvt_pk_bf16_f32 v203, v78, v79
	v_cvt_pk_bf16_f32 v204, v72, v73
	v_cvt_pk_bf16_f32 v205, v74, v75
	global_store_dwordx4 v143, v[202:205], s[8:9]
	v_lshlrev_b32_e32 v228, 16, v206
	v_and_b32_e32 v229, 0xffff0000, v206
	v_lshlrev_b32_e32 v236, 16, v214
	v_and_b32_e32 v237, 0xffff0000, v214
	v_lshlrev_b32_e32 v230, 16, v207
	v_and_b32_e32 v231, 0xffff0000, v207
	v_lshlrev_b32_e32 v238, 16, v215
	v_and_b32_e32 v239, 0xffff0000, v215
	v_lshlrev_b32_e32 v232, 16, v208
	v_and_b32_e32 v233, 0xffff0000, v208
	v_lshlrev_b32_e32 v240, 16, v216
	v_and_b32_e32 v241, 0xffff0000, v216
	v_lshlrev_b32_e32 v234, 16, v209
	v_and_b32_e32 v235, 0xffff0000, v209
	v_lshlrev_b32_e32 v242, 16, v217
	v_and_b32_e32 v243, 0xffff0000, v217
	v_pk_fma_f32 v[64:65], v[64:65], v[228:229], v[236:237]
	v_pk_fma_f32 v[66:67], v[66:67], v[230:231], v[238:239]
	v_pk_fma_f32 v[68:69], v[68:69], v[232:233], v[240:241]
	v_pk_fma_f32 v[70:71], v[70:71], v[234:235], v[242:243]
	v_cvt_pk_bf16_f32 v206, v64, v65
	v_cvt_pk_bf16_f32 v207, v66, v67
	v_cvt_pk_bf16_f32 v208, v68, v69
	v_cvt_pk_bf16_f32 v209, v70, v71
	global_store_dwordx4 v143, v[206:209], s[8:9] offset:256
	v_add_u32_e32 v141, 0x58000, v140
	global_load_dwordx4 v[202:205], v141, s[12:13]
	global_load_dwordx4 v[206:209], v141, s[12:13] offset:256
	global_load_dwordx4 v[210:213], v141, s[8:9]
	global_load_dwordx4 v[214:217], v141, s[8:9] offset:256
	s_waitcnt vmcnt(18)
	v_add_u32_e32 v143, 0x40000, v140
	v_lshlrev_b32_e32 v228, 16, v154
	v_and_b32_e32 v229, 0xffff0000, v154
	v_lshlrev_b32_e32 v236, 16, v162
	v_and_b32_e32 v237, 0xffff0000, v162
	v_lshlrev_b32_e32 v230, 16, v155
	v_and_b32_e32 v231, 0xffff0000, v155
	v_lshlrev_b32_e32 v238, 16, v163
	v_and_b32_e32 v239, 0xffff0000, v163
	v_lshlrev_b32_e32 v232, 16, v156
	v_and_b32_e32 v233, 0xffff0000, v156
	v_lshlrev_b32_e32 v240, 16, v164
	v_and_b32_e32 v241, 0xffff0000, v164
	v_lshlrev_b32_e32 v234, 16, v157
	v_and_b32_e32 v235, 0xffff0000, v157
	v_lshlrev_b32_e32 v242, 16, v165
	v_and_b32_e32 v243, 0xffff0000, v165
	v_pk_fma_f32 v[60:61], v[60:61], v[228:229], v[236:237]
	v_pk_fma_f32 v[62:63], v[62:63], v[230:231], v[238:239]
	v_pk_fma_f32 v[56:57], v[56:57], v[232:233], v[240:241]
	v_pk_fma_f32 v[58:59], v[58:59], v[234:235], v[242:243]
	v_cvt_pk_bf16_f32 v154, v60, v61
	v_cvt_pk_bf16_f32 v155, v62, v63
	v_cvt_pk_bf16_f32 v156, v56, v57
	v_cvt_pk_bf16_f32 v157, v58, v59
	global_store_dwordx4 v143, v[154:157], s[8:9]
	v_lshlrev_b32_e32 v228, 16, v158
	v_and_b32_e32 v229, 0xffff0000, v158
	v_lshlrev_b32_e32 v236, 16, v166
	v_and_b32_e32 v237, 0xffff0000, v166
	v_lshlrev_b32_e32 v230, 16, v159
	v_and_b32_e32 v231, 0xffff0000, v159
	v_lshlrev_b32_e32 v238, 16, v167
	v_and_b32_e32 v239, 0xffff0000, v167
	v_lshlrev_b32_e32 v232, 16, v160
	v_and_b32_e32 v233, 0xffff0000, v160
	v_lshlrev_b32_e32 v240, 16, v168
	v_and_b32_e32 v241, 0xffff0000, v168
	v_lshlrev_b32_e32 v234, 16, v161
	v_and_b32_e32 v235, 0xffff0000, v161
	v_lshlrev_b32_e32 v242, 16, v169
	v_and_b32_e32 v243, 0xffff0000, v169
	v_pk_fma_f32 v[48:49], v[48:49], v[228:229], v[236:237]
	v_pk_fma_f32 v[50:51], v[50:51], v[230:231], v[238:239]
	v_pk_fma_f32 v[52:53], v[52:53], v[232:233], v[240:241]
	v_pk_fma_f32 v[54:55], v[54:55], v[234:235], v[242:243]
	v_cvt_pk_bf16_f32 v158, v48, v49
	v_cvt_pk_bf16_f32 v159, v50, v51
	v_cvt_pk_bf16_f32 v160, v52, v53
	v_cvt_pk_bf16_f32 v161, v54, v55
	global_store_dwordx4 v143, v[158:161], s[8:9] offset:256
	s_waitcnt vmcnt(14)
; __device__ __forceinline__ u32x4 pack8(const f32x4 a, const f32x4 b) { u32x4 w; w.x = cvt_pk_bf16(a[0], a[1]); w.y = cvt_pk_bf16(a[2], a[3]); w.z = cvt_pk_bf16(b[0], b[1]); w.w = cvt_pk_bf16(b[2], b[3]); return w; }
; __device__ __forceinline__ void unpack8(const u32x4 w, f32x4& a, f32x4& b) { a = (f32x4){bflo(w.x), bfhi(w.x), bflo(w.y), bfhi(w.y)}; b = (f32x4){bflo(w.z), bfhi(w.z), bflo(w.w), bfhi(w.w)}; }
;     __device__ __forceinline__ void operator()(const f32x4 (&acc)[2][2][4][2], const Unit& u, int wr, int wc, int fr, int fq) const {
;         const int rbase = u.pm * 256 + wr * 64 + fr, cb = u.pn * 256 + wc * 32 + fq * 8;
; #pragma unroll
;         for (int ai = 0; ai < 2; ++ai)
; #pragma unroll
;             for (int m = 0; m < 4; ++m) { const size_t ro = (size_t)(rbase + ai * 128 + m * 16) * 1024 + cb;
; #pragma unroll
;                 for (int bj = 0; bj < 2; ++bj) { f32x4 g0, g1; unpack8(*(const u32x4*)(G + ro + bj * 128), g0, g1);
;                     f32x4 v0 = acc[ai][bj][m][0] * g0, v1 = acc[ai][bj][m][1] * g1;
;                     if (!FIRST) { f32x4 o0, o1; unpack8(*(const u32x4*)(O + ro + bj * 128), o0, o1); v0 += o0; v1 += o1; }
;                     *(u32x4*)(O + ro + bj * 128) = pack8(v0, v1); }
;                 asm volatile("" ::: "memory"); }
	v_add_u32_e32 v143, 0x48000, v140
	v_lshlrev_b32_e32 v228, 16, v170
	v_and_b32_e32 v229, 0xffff0000, v170
	v_lshlrev_b32_e32 v236, 16, v178
	v_and_b32_e32 v237, 0xffff0000, v178
	v_lshlrev_b32_e32 v230, 16, v171
	v_and_b32_e32 v231, 0xffff0000, v171
	v_lshlrev_b32_e32 v238, 16, v179
	v_and_b32_e32 v239, 0xffff0000, v179
	v_lshlrev_b32_e32 v232, 16, v172
	v_and_b32_e32 v233, 0xffff0000, v172
	v_lshlrev_b32_e32 v240, 16, v180
	v_and_b32_e32 v241, 0xffff0000, v180
	v_lshlrev_b32_e32 v234, 16, v173
	v_and_b32_e32 v235, 0xffff0000, v173
	v_lshlrev_b32_e32 v242, 16, v181
	v_and_b32_e32 v243, 0xffff0000, v181
	v_pk_fma_f32 v[44:45], v[44:45], v[228:229], v[236:237]
	v_pk_fma_f32 v[46:47], v[46:47], v[230:231], v[238:239]
	v_pk_fma_f32 v[40:41], v[40:41], v[232:233], v[240:241]
	v_pk_fma_f32 v[42:43], v[42:43], v[234:235], v[242:243]
	v_cvt_pk_bf16_f32 v170, v44, v45
	v_cvt_pk_bf16_f32 v171, v46, v47
	v_cvt_pk_bf16_f32 v172, v40, v41
	v_cvt_pk_bf16_f32 v173, v42, v43
	global_store_dwordx4 v143, v[170:173], s[8:9]
	v_lshlrev_b32_e32 v228, 16, v174
	v_and_b32_e32 v229, 0xffff0000, v174
	v_lshlrev_b32_e32 v236, 16, v182
	v_and_b32_e32 v237, 0xffff0000, v182
	v_lshlrev_b32_e32 v230, 16, v175
	v_and_b32_e32 v231, 0xffff0000, v175
	v_lshlrev_b32_e32 v238, 16, v183
	v_and_b32_e32 v239, 0xffff0000, v183
	v_lshlrev_b32_e32 v232, 16, v176
	v_and_b32_e32 v233, 0xffff0000, v176
	v_lshlrev_b32_e32 v240, 16, v184
	v_and_b32_e32 v241, 0xffff0000, v184
	v_lshlrev_b32_e32 v234, 16, v177
	v_and_b32_e32 v235, 0xffff0000, v177
	v_lshlrev_b32_e32 v242, 16, v185
	v_and_b32_e32 v243, 0xffff0000, v185
	v_pk_fma_f32 v[32:33], v[32:33], v[228:229], v[236:237]
	v_pk_fma_f32 v[34:35], v[34:35], v[230:231], v[238:239]
	v_pk_fma_f32 v[36:37], v[36:37], v[232:233], v[240:241]
	v_pk_fma_f32 v[38:39], v[38:39], v[234:235], v[242:243]
	v_cvt_pk_bf16_f32 v174, v32, v33
	v_cvt_pk_bf16_f32 v175, v34, v35
	v_cvt_pk_bf16_f32 v176, v36, v37
	v_cvt_pk_bf16_f32 v177, v38, v39
	global_store_dwordx4 v143, v[174:177], s[8:9] offset:256
	s_waitcnt vmcnt(10)
	v_add_u32_e32 v143, 0x50000, v140
	v_lshlrev_b32_e32 v228, 16, v186
	v_and_b32_e32 v229, 0xffff0000, v186
	v_lshlrev_b32_e32 v236, 16, v194
	v_and_b32_e32 v237, 0xffff0000, v194
	v_lshlrev_b32_e32 v230, 16, v187
	v_and_b32_e32 v231, 0xffff0000, v187
	v_lshlrev_b32_e32 v238, 16, v195
	v_and_b32_e32 v239, 0xffff0000, v195
	v_lshlrev_b32_e32 v232, 16, v188
	v_and_b32_e32 v233, 0xffff0000, v188
	v_lshlrev_b32_e32 v240, 16, v196
	v_and_b32_e32 v241, 0xffff0000, v196
	v_lshlrev_b32_e32 v234, 16, v189
	v_and_b32_e32 v235, 0xffff0000, v189
	v_lshlrev_b32_e32 v242, 16, v197
	v_and_b32_e32 v243, 0xffff0000, v197
	v_pk_fma_f32 v[28:29], v[28:29], v[228:229], v[236:237]
	v_pk_fma_f32 v[30:31], v[30:31], v[230:231], v[238:239]
	v_pk_fma_f32 v[24:25], v[24:25], v[232:233], v[240:241]
	v_pk_fma_f32 v[26:27], v[26:27], v[234:235], v[242:243]
	v_cvt_pk_bf16_f32 v186, v28, v29
	v_cvt_pk_bf16_f32 v187, v30, v31
	v_cvt_pk_bf16_f32 v188, v24, v25
	v_cvt_pk_bf16_f32 v189, v26, v27
	global_store_dwordx4 v143, v[186:189], s[8:9]
	v_lshlrev_b32_e32 v228, 16, v190
	v_and_b32_e32 v229, 0xffff0000, v190
	v_lshlrev_b32_e32 v236, 16, v198
	v_and_b32_e32 v237, 0xffff0000, v198
	v_lshlrev_b32_e32 v230, 16, v191
	v_and_b32_e32 v231, 0xffff0000, v191
	v_lshlrev_b32_e32 v238, 16, v199
	v_and_b32_e32 v239, 0xffff0000, v199
	v_lshlrev_b32_e32 v232, 16, v192
	v_and_b32_e32 v233, 0xffff0000, v192
	v_lshlrev_b32_e32 v240, 16, v200
	v_and_b32_e32 v241, 0xffff0000, v200
	v_lshlrev_b32_e32 v234, 16, v193
	v_and_b32_e32 v235, 0xffff0000, v193
	v_lshlrev_b32_e32 v242, 16, v201
	v_and_b32_e32 v243, 0xffff0000, v201
	v_pk_fma_f32 v[16:17], v[16:17], v[228:229], v[236:237]
	v_pk_fma_f32 v[18:19], v[18:19], v[230:231], v[238:239]
	v_pk_fma_f32 v[20:21], v[20:21], v[232:233], v[240:241]
	v_pk_fma_f32 v[22:23], v[22:23], v[234:235], v[242:243]
	v_cvt_pk_bf16_f32 v190, v16, v17
	v_cvt_pk_bf16_f32 v191, v18, v19
	v_cvt_pk_bf16_f32 v192, v20, v21
	v_cvt_pk_bf16_f32 v193, v22, v23
	global_store_dwordx4 v143, v[190:193], s[8:9] offset:256
	s_waitcnt vmcnt(6)
	v_add_u32_e32 v143, 0x58000, v140
	v_lshlrev_b32_e32 v228, 16, v202
	v_and_b32_e32 v229, 0xffff0000, v202
	v_lshlrev_b32_e32 v236, 16, v210
	v_and_b32_e32 v237, 0xffff0000, v210
	v_lshlrev_b32_e32 v230, 16, v203
	v_and_b32_e32 v231, 0xffff0000, v203
	v_lshlrev_b32_e32 v238, 16, v211
	v_and_b32_e32 v239, 0xffff0000, v211
	v_lshlrev_b32_e32 v232, 16, v204
	v_and_b32_e32 v233, 0xffff0000, v204
	v_lshlrev_b32_e32 v240, 16, v212
	v_and_b32_e32 v241, 0xffff0000, v212
	v_lshlrev_b32_e32 v234, 16, v205
	v_and_b32_e32 v235, 0xffff0000, v205
	v_lshlrev_b32_e32 v242, 16, v213
	v_and_b32_e32 v243, 0xffff0000, v213
	v_pk_fma_f32 v[12:13], v[12:13], v[228:229], v[236:237]
	v_pk_fma_f32 v[14:15], v[14:15], v[230:231], v[238:239]
	v_pk_fma_f32 v[8:9], v[8:9], v[232:233], v[240:241]
	v_pk_fma_f32 v[10:11], v[10:11], v[234:235], v[242:243]
	v_cvt_pk_bf16_f32 v202, v12, v13
	v_cvt_pk_bf16_f32 v203, v14, v15
	v_cvt_pk_bf16_f32 v204, v8, v9
	v_cvt_pk_bf16_f32 v205, v10, v11
	global_store_dwordx4 v143, v[202:205], s[8:9]
	v_lshlrev_b32_e32 v228, 16, v206
	v_and_b32_e32 v229, 0xffff0000, v206
	v_lshlrev_b32_e32 v236, 16, v214
	v_and_b32_e32 v237, 0xffff0000, v214
	v_lshlrev_b32_e32 v230, 16, v207
	v_and_b32_e32 v231, 0xffff0000, v207
	v_lshlrev_b32_e32 v238, 16, v215
	v_and_b32_e32 v239, 0xffff0000, v215
	v_lshlrev_b32_e32 v232, 16, v208
	v_and_b32_e32 v233, 0xffff0000, v208
	v_lshlrev_b32_e32 v240, 16, v216
	v_and_b32_e32 v241, 0xffff0000, v216
	v_lshlrev_b32_e32 v234, 16, v209
	v_and_b32_e32 v235, 0xffff0000, v209
	v_lshlrev_b32_e32 v242, 16, v217
	v_and_b32_e32 v243, 0xffff0000, v217
	v_pk_fma_f32 v[4:5], v[4:5], v[228:229], v[236:237]
	v_pk_fma_f32 v[6:7], v[6:7], v[230:231], v[238:239]
	v_pk_fma_f32 v[0:1], v[0:1], v[232:233], v[240:241]
	v_pk_fma_f32 v[2:3], v[2:3], v[234:235], v[242:243]
	v_cvt_pk_bf16_f32 v206, v4, v5
	v_cvt_pk_bf16_f32 v207, v6, v7
	v_cvt_pk_bf16_f32 v208, v0, v1
	v_cvt_pk_bf16_f32 v209, v2, v3
	global_store_dwordx4 v143, v[206:209], s[8:9] offset:256
	s_andn2_b64 vcc, exec, s[4:5]
	s_mov_b64 s[4:5], -1
	s_cbranch_vccnz .LBB0_1351
	s_andn2_b64 vcc, exec, s[10:11]
	s_cbranch_vccnz .LBB0_1350
	s_barrier
	s_branch .LBB0_1350
